# prep0: rope cos/sin computed for a wave's first two tokens and reused (grid row alternates, grid col fixed) + 1x8 scan
# speedup vs baseline: 1.0174x; 1.0066x over previous
; __device__ __forceinline__ int tidx() { int t = threadIdx.x; asm volatile("" : "+v"(t)); return t; }
; __device__ __forceinline__ const float* kin(int i) { KArgs* k = (KArgs*)__builtin_amdgcn_kernarg_segment_ptr(); return *(const float* const volatile __attribute__((address_space(4)))*)&k->in[i]; }
; #define c opq(blockIdx.x)
; __device__ __forceinline__ void phase_prep0() {
;     const int tid = tidx(), lane = tid & 63, wid = tid >> 6, l7 = lane & 7; const int gw = blockIdx.x * 8 + wid, NGW = gridDim.x * 8;
;     const bf16_t* P = (const bf16_t*)(kws() + WS_P);
;     bf16_t* Q0 = (bf16_t*)((unsigned char*)kout() + DO_Q0); bf16_t* KALL = (bf16_t*)(kws() + WS_KALL); bf16_t* VALL = (bf16_t*)(kws() + WS_VALL);
;     bf16_t* XR = (bf16_t*)(kws() + WS_XR); bf16_t* XK = (bf16_t*)(kws() + WS_XK); bf16_t* XV = (bf16_t*)(kws() + WS_XV); bf16_t* KK = (bf16_t*)(kws() + WS_KK); bf16_t* AP = (bf16_t*)(kws() + WS_AP);
;     float muv[7][8], kkc[2][8], qn[8], kn[8];
;     { const float* mu = kin(9); const float* k_k = kin(19); const float* qnp = kin(24); const float* knp = kin(25);
; #pragma unroll
;       for (int p = 0; p < 7; ++p)
; #pragma unroll
;           for (int e = 0; e < 8; ++e) { const int c = p * 512 + lane * 8 + e; muv[p][e] = c < 3488 ? mu[c] : 0.f; }
; #pragma unroll
;       for (int p = 0; p < 2; ++p)
; #pragma unroll
;           for (int e = 0; e < 8; ++e) kkc[p][e] = k_k[p * 512 + lane * 8 + e];
; #pragma unroll
;       for (int e = 0; e < 8; ++e) { qn[e] = qnp[l7 * 8 + e]; kn[e] = knp[l7 * 8 + e]; } }
;     for (int row = gw; row < NT; row += NGW) {
;         const bf16_t* prow = P + (size_t)row * INP;
;         const bool isc = row >= NLAT; int b, t = 0, s = 0, grow = 0, gcol = 0;
;         if (!isc) { b = row >> 12; t = row & 4095; grow = t >> 6; gcol = t & 63; } else { b = (row - NLAT) >> 8; s = (row - NLAT) & 255; }
;         float cs[8], sn[8];
; #pragma unroll
;         for (int e = 0; e < 8; ++e) { cs[e] = 1.f; sn[e] = 0.f; }
;         if (!isc) {
; #pragma unroll
;             for (int e = 0; e < 8; ++e) { const int i = 8 * (l7 & 3) + e, mm = i & 15; const float pos = (float)(i < 16 ? grow : gcol); const float ang = pos * exp2f(-(float)mm * 0.8304820237218406f); cs[e] = cosf(ang); sn[e] = sinf(ang); } }
.LBB0_276:
	s_or_b64 exec, exec, s[30:31]
	v_ashrrev_i32_e32 v48, 6, v81
	v_readlane_b32 s0, v254, 2
	s_mul_hi_i32 s63, s78, 0x2800
	s_mul_i32 s62, s78, 0x2800
	v_add_u32_e32 v102, s0, v48
	s_movk_i32 s0, 0x4400
	v_cmp_gt_i32_e32 vcc, s0, v102
	s_and_saveexec_b64 s[2:3], vcc
	s_cbranch_execz .LBB0_499
	v_and_b32_e32 v82, 7, v81
	v_lshlrev_b32_e32 v76, 5, v82
	s_waitcnt vmcnt(11)
	v_mov_b32_e32 v83, v2
	s_waitcnt vmcnt(10)
	v_mov_b32_e32 v2, v6
	s_waitcnt vmcnt(9)
	v_mov_b32_e32 v6, v10
	s_waitcnt vmcnt(8)
	v_mov_b32_e32 v10, v14
	s_waitcnt vmcnt(6)
	v_mov_b32_e32 v14, v22
	v_mov_b32_e32 v22, v18
	s_waitcnt vmcnt(5)
	v_mov_b32_e32 v18, v26
	s_waitcnt vmcnt(4)
	v_mov_b32_e32 v26, v30
	s_waitcnt vmcnt(2)
	v_mov_b32_e32 v30, v38
	v_mov_b32_e32 v38, v34
	s_waitcnt vmcnt(0)
	v_mov_b32_e32 v34, v46
	v_mov_b32_e32 v46, v42
	v_lshlrev_b32_e32 v42, 2, v56
	global_load_dwordx4 v[48:51], v76, s[28:29] offset:16
	global_load_dwordx4 v[52:55], v76, s[28:29]
	global_load_dwordx4 v[56:59], v42, s[26:27] offset:2064
	global_load_dwordx4 v[60:63], v42, s[26:27] offset:2048
	global_load_dwordx4 v[64:67], v42, s[26:27] offset:16
	global_load_dwordx4 v[68:71], v42, s[26:27]
	global_load_dwordx4 v[72:75], v76, s[24:25] offset:16
	s_nop 0
	global_load_dwordx4 v[76:79], v76, s[24:25]
	v_lshlrev_b32_e32 v42, 3, v81
	v_bfe_u32 v143, v81, 3, 2
	v_and_b32_e32 v42, 8, v42
	v_and_b32_e32 v81, 2, v81
	v_cmp_eq_u32_e64 s[46:47], 0, v81
	v_cvt_f32_ubyte0_e32 v81, v42
	v_lshlrev_b32_e32 v100, 3, v82
	v_cmp_gt_u32_e64 s[38:39], 4, v82
	v_mul_f32_e32 v82, 0xbf549a78, v81
	s_mov_b32 s0, 0xc2fc0000
	v_cmp_gt_f32_e32 vcc, s0, v82
	v_mov_b32_e32 v82, 0x42800000
	v_not_b32_e32 v144, 63
	v_cndmask_b32_e32 v84, 0, v82, vcc
	v_fmac_f32_e32 v84, 0xbf549a78, v81
	v_exp_f32_e32 v81, v84
	v_cndmask_b32_e32 v84, 0, v144, vcc
	v_ashrrev_i32_e32 v103, 31, v102
	s_add_u32 s4, s4, 0x25c00000
	v_ldexp_f32 v145, v81, v84
	v_or_b32_e32 v81, 1, v42
	v_cvt_f32_ubyte0_e32 v81, v81
	v_mul_f32_e32 v84, 0xbf549a78, v81
	v_cmp_gt_f32_e32 vcc, s0, v84
	s_addc_u32 s5, s5, 0
	v_cmp_gt_u32_e64 s[40:41], 32, v80
	v_cndmask_b32_e32 v84, 0, v82, vcc
	v_fmac_f32_e32 v84, 0xbf549a78, v81
	v_exp_f32_e32 v81, v84
	v_cndmask_b32_e32 v84, 0, v144, vcc
	v_cmp_lt_u32_e64 s[42:43], 31, v80
	v_cmp_lt_u32_e64 s[44:45], 15, v80
	v_ldexp_f32 v146, v81, v84
	v_or_b32_e32 v81, 2, v42
	v_cvt_f32_ubyte0_e32 v81, v81
	v_mul_f32_e32 v84, 0xbf549a78, v81
	v_cmp_gt_f32_e32 vcc, s0, v84
	s_add_u32 s12, s12, 0x25300000
	s_addc_u32 s13, s13, 0
	v_cndmask_b32_e32 v84, 0, v82, vcc
	v_fmac_f32_e32 v84, 0xbf549a78, v81
	v_exp_f32_e32 v81, v84
	v_cndmask_b32_e32 v84, 0, v144, vcc
	v_mov_b32_e32 v105, 0
	s_ashr_i32 s79, s78, 31
	v_ldexp_f32 v147, v81, v84
	v_or_b32_e32 v81, 3, v42
	v_cvt_f32_ubyte0_e32 v81, v81
	v_mul_f32_e32 v84, 0xbf549a78, v81
	v_cmp_gt_f32_e32 vcc, s0, v84
	s_lshl_b64 s[64:65], s[78:79], 11
	s_lshl_b64 s[66:67], s[78:79], 10
	v_cndmask_b32_e32 v84, 0, v82, vcc
	v_fmac_f32_e32 v84, 0xbf549a78, v81
	v_exp_f32_e32 v81, v84
	v_cndmask_b32_e32 v84, 0, v144, vcc
	s_mov_b64 s[68:69], 0
	s_mov_b32 s6, 0xfe5163ab
	v_ldexp_f32 v148, v81, v84
	v_or_b32_e32 v81, 4, v42
	v_cvt_f32_ubyte0_e32 v81, v81
	v_mul_f32_e32 v84, 0xbf549a78, v81
	v_cmp_gt_f32_e32 vcc, s0, v84
	s_mov_b32 s7, 0x3c439041
	s_mov_b32 s24, 0xfc2757d1
	v_cndmask_b32_e32 v84, 0, v82, vcc
	v_fmac_f32_e32 v84, 0xbf549a78, v81
	v_exp_f32_e32 v81, v84
	v_cndmask_b32_e32 v84, 0, v144, vcc
	s_mov_b32 s25, 0x4e441529
	s_mov_b32 s26, 0xa2f9836e
	v_ldexp_f32 v149, v81, v84
	v_or_b32_e32 v81, 5, v42
	v_cvt_f32_ubyte0_e32 v81, v81
	v_mul_f32_e32 v84, 0xbf549a78, v81
	v_cmp_gt_f32_e32 vcc, s0, v84
	s_waitcnt vmcnt(4)
	v_mov_b32_e32 v106, v61
	v_mov_b32_e32 v61, v62
	v_cndmask_b32_e32 v84, 0, v82, vcc
	v_fmac_f32_e32 v84, 0xbf549a78, v81
	v_exp_f32_e32 v81, v84
	v_cndmask_b32_e32 v84, 0, v144, vcc
	v_mov_b32_e32 v62, v57
	v_mov_b32_e32 v57, v58
	v_ldexp_f32 v150, v81, v84
	v_or_b32_e32 v81, 6, v42
	v_cvt_f32_ubyte0_e32 v81, v81
	v_mul_f32_e32 v84, 0xbf549a78, v81
	v_cmp_gt_f32_e32 vcc, s0, v84
	v_or_b32_e32 v42, 7, v42
	v_cvt_f32_ubyte0_e32 v42, v42
	v_cndmask_b32_e32 v84, 0, v82, vcc
	v_fmac_f32_e32 v84, 0xbf549a78, v81
	v_exp_f32_e32 v81, v84
	v_cndmask_b32_e32 v84, 0, v144, vcc
	s_waitcnt vmcnt(2)
	v_mov_b32_e32 v58, v69
	v_mov_b32_e32 v69, v70
	v_ldexp_f32 v151, v81, v84
	v_mul_f32_e32 v81, 0xbf549a78, v42
	v_cmp_gt_f32_e32 vcc, s0, v81
	s_movk_i32 s0, 0xffeb
	v_mov_b32_e32 v70, v65
	v_cndmask_b32_e32 v81, 0, v82, vcc
	v_fmac_f32_e32 v81, 0xbf549a78, v42
	v_exp_f32_e32 v42, v81
	v_cndmask_b32_e32 v81, 0, v144, vcc
	v_mov_b32_e32 v65, v66
	v_lshlrev_b32_e32 v66, 4, v80
	v_ldexp_f32 v152, v42, v81
	v_subrev_u32_e32 v42, 52, v80
	v_cmp_lt_u32_e64 s[48:49], s0, v42
	v_mov_b32_e32 v42, v41
	v_mov_b32_e32 v41, v46
	v_mov_b32_e32 v46, v45
	v_mov_b32_e32 v45, v34
	v_mov_b32_e32 v34, v33
	v_mov_b32_e32 v33, v38
	v_mov_b32_e32 v38, v37
	v_mov_b32_e32 v37, v30
	v_mov_b32_e32 v30, v29
	v_mov_b32_e32 v29, v26
	v_mov_b32_e32 v26, v25
	v_mov_b32_e32 v25, v18
	v_mov_b32_e32 v18, v17
	v_mov_b32_e32 v17, v22
	v_mov_b32_e32 v22, v21
	v_mov_b32_e32 v21, v14
	v_mov_b32_e32 v14, v13
	v_mov_b32_e32 v13, v10
	v_mov_b32_e32 v10, v9
	v_mov_b32_e32 v9, v6
	v_mov_b32_e32 v6, v5
	v_mov_b32_e32 v5, v2
	v_mov_b32_e32 v2, v1
	v_mov_b32_e32 v1, v83
	v_lshlrev_b64 v[82:83], 10, v[102:103]
	v_lshlrev_b64 v[80:81], 11, v[102:103]
	v_lshl_add_u64 v[82:83], s[20:21], 0, v[82:83]
	s_mov_b64 s[0:1], 0x24200000
	v_lshl_add_u64 v[108:109], s[22:23], 0, v[80:81]
	v_lshl_add_u64 v[110:111], s[18:19], 0, v[80:81]
	v_lshl_add_u64 v[112:113], v[82:83], 0, s[0:1]
	v_lshl_add_u64 v[114:115], s[14:15], 0, v[80:81]
	v_lshl_add_u64 v[116:117], s[16:17], 0, v[80:81]
	v_lshl_add_u64 v[118:119], s[10:11], 0, v[80:81]
	s_movk_i32 s0, 0x2800
	v_mov_b64_e32 v[80:81], s[8:9]
	v_mad_i64_i32 v[120:121], s[0:1], v102, s0, v[80:81]
	v_mov_b32_e32 v107, v63
	v_mov_b32_e32 v63, v59
	v_mov_b32_e32 v59, v71
	v_mov_b32_e32 v71, v67
	v_mov_b32_e32 v67, v105
	s_brev_b32 s0, 18
	s_mov_b32 s1, 0x800000
	s_mov_b32 s22, 0xdb629599
	s_mov_b32 s23, 0xf534ddc0
	s_mov_b32 s27, 0x3fc90fda
	v_mov_b32_e32 v103, 0x3c0881c4
	v_mov_b32_e32 v153, 0xbab64f3b
	s_brev_b32 s28, 1
	s_mov_b32 s29, 0x7f800000
	s_mov_b32 s30, 0xffff0000
	v_mov_b32_e32 v154, 0x358637bd
	s_mov_b32 s70, 0x3e38aa3b
	s_movk_i32 s31, 0x7fff
	s_mov_b32 s33, 0x3f200000
	s_mov_b32 s34, 0x3fb8aa3b
	s_mov_b32 s35, 0xc2ce8ed0
	s_mov_b32 s36, 0x42b17218
	v_mov_b32_e32 v155, 0x3ca908c9
	s_brev_b32 s37, -2
	v_not_b32_e32 v156, 31
	v_mov_b32_e32 v157, 0x7fc00000
	v_mov_b32_e32 v158, 0x7f800000
	s_mov_b32 s98, 0
	s_branch .LBB0_280

; __device__ __forceinline__ void phase_prep0() {
;     ...
;     for (int row = gw; row < NT; row += NGW) {
;         const bf16_t* prow = P + (size_t)row * INP;
;         const bool isc = row >= NLAT; int b, t = 0, s = 0, grow = 0, gcol = 0;
;         if (!isc) { b = row >> 12; t = row & 4095; grow = t >> 6; gcol = t & 63; } else { b = (row - NLAT) >> 8; s = (row - NLAT) & 255; }
;         float cs[8], sn[8];
; #pragma unroll
;         for (int e = 0; e < 8; ++e) { cs[e] = 1.f; sn[e] = 0.f; }
;         if (!isc) {
; #pragma unroll
;             for (int e = 0; e < 8; ++e) { const int i = 8 * (l7 & 3) + e, mm = i & 15; const float pos = (float)(i < 16 ? grow : gcol); const float ang = pos * exp2f(-(float)mm * 0.8304820237218406f); cs[e] = cosf(ang); sn[e] = sinf(ang); } }
.LBB0_280:
	s_movk_i32 s8, 0x3fff
	v_cmp_lt_i32_e64 s[52:53], s8, v102
	s_movk_i32 s8, 0x4000
	v_cmp_gt_i32_e64 s[50:51], s8, v102
	s_and_saveexec_b64 s[8:9], s[50:51]
	s_xor_b64 s[8:9], exec, s[8:9]
	v_ashrrev_i32_e32 v162, 12, v102
	v_and_b32_e32 v163, 0xfff, v102
	v_bfe_u32 v159, v102, 6, 6
	v_and_b32_e32 v160, 63, v102
	s_or_saveexec_b64 s[8:9], s[8:9]
	v_mov_b32_e32 v87, 0
	v_mov_b32_e32 v161, 0
	s_xor_b64 exec, exec, s[8:9]
	v_add_u32_e32 v80, 0xffffc000, v102
	v_lshrrev_b32_e32 v162, 8, v80
	v_and_b32_e32 v161, 0xff, v102
	v_mov_b32_e32 v160, 0
	v_mov_b32_e32 v159, 0
	v_mov_b32_e32 v163, 0
	s_or_b64 exec, exec, s[8:9]
	v_mov_b32_e32 v85, 1.0
	v_mov_b32_e32 v86, 0
	v_mov_b32_e32 v84, v85
	v_mov_b32_e32 v91, 0
	v_mov_b32_e32 v90, 0
	v_mov_b32_e32 v89, v85
	v_mov_b32_e32 v88, v85
	v_mov_b32_e32 v95, 0
	v_mov_b32_e32 v94, 0
	v_mov_b32_e32 v93, v85
	v_mov_b32_e32 v92, v85
	v_mov_b32_e32 v99, 0
	v_mov_b32_e32 v98, 0
	v_mov_b32_e32 v97, v85
	v_mov_b32_e32 v96, v85
	s_and_saveexec_b64 s[14:15], s[50:51]
	s_cbranch_execz .LBB0_350
	s_cmp_ge_u32 s98, 2
	s_cbranch_scc1 .Lprep_reuse
	v_cndmask_b32_e64 v80, v160, v159, s[46:47]
	v_cvt_f32_u32_e32 v84, v80
	v_mul_f32_e32 v80, v145, v84
	v_lshrrev_b32_e32 v81, 23, v80
	v_and_b32_e32 v82, 0x7fffff, v80
	v_cmp_ngt_f32_e32 vcc, s0, v80
	v_add_u32_e32 v86, 0xffffff88, v81
	v_or_b32_e32 v85, 0x800000, v82
	s_and_saveexec_b64 s[8:9], vcc
	s_xor_b64 s[8:9], exec, s[8:9]
	s_cbranch_execz .LBB0_287
	v_cmp_lt_u32_e64 s[54:55], 63, v86
	s_nop 1
	v_cndmask_b32_e64 v81, 0, v144, s[54:55]
	v_add_u32_e32 v81, v81, v86
	v_cmp_lt_u32_e64 s[56:57], 31, v81
	s_nop 1
	v_cndmask_b32_e64 v82, 0, v156, s[56:57]
	v_add_u32_e32 v81, v82, v81
	v_cmp_lt_u32_e64 s[58:59], 31, v81
	s_nop 1
	v_cndmask_b32_e64 v82, 0, v156, s[58:59]
	v_add_u32_e32 v81, v82, v81
	v_mad_u64_u32 v[82:83], s[10:11], v85, s6, 0
	v_mov_b32_e32 v104, v83
	v_mad_u64_u32 v[88:89], s[10:11], v85, s7, v[104:105]
	v_mov_b32_e32 v104, v89
	v_mad_u64_u32 v[90:91], s[10:11], v85, s22, v[104:105]
	v_mov_b32_e32 v104, v91
	v_mad_u64_u32 v[92:93], s[10:11], v85, s23, v[104:105]
	v_mov_b32_e32 v104, v93
	v_mad_u64_u32 v[94:95], s[10:11], v85, s24, v[104:105]
	v_mov_b32_e32 v104, v95
	v_mad_u64_u32 v[96:97], s[10:11], v85, s25, v[104:105]
	v_mov_b32_e32 v104, v97
	v_mad_u64_u32 v[98:99], s[10:11], v85, s26, v[104:105]
	v_cndmask_b32_e64 v83, v96, v92, s[54:55]
	v_cndmask_b32_e64 v87, v98, v94, s[54:55]
	v_cndmask_b32_e64 v91, v99, v96, s[54:55]
	v_cndmask_b32_e64 v89, v87, v83, s[56:57]
	v_cndmask_b32_e64 v87, v91, v87, s[56:57]
	v_cndmask_b32_e64 v91, v94, v90, s[54:55]
	v_cndmask_b32_e64 v83, v83, v91, s[56:57]
	v_cndmask_b32_e64 v87, v87, v89, s[58:59]
	v_cndmask_b32_e64 v89, v89, v83, s[58:59]
	v_sub_u32_e32 v93, 32, v81
	v_alignbit_b32 v94, v87, v89, v93
	v_cmp_eq_u32_e64 s[60:61], 0, v81
	v_cndmask_b32_e64 v82, v90, v82, s[54:55]
	s_nop 0
	v_cndmask_b32_e64 v81, v94, v87, s[60:61]
	v_cndmask_b32_e64 v87, v92, v88, s[54:55]
	v_cndmask_b32_e64 v88, v91, v87, s[56:57]
	v_cndmask_b32_e64 v83, v83, v88, s[58:59]
	v_alignbit_b32 v91, v89, v83, v93
	v_cndmask_b32_e64 v89, v91, v89, s[60:61]
	v_bfe_u32 v94, v81, 29, 1
	v_cndmask_b32_e64 v82, v87, v82, s[56:57]
	v_alignbit_b32 v91, v81, v89, 30
	v_sub_u32_e32 v95, 0, v94
	v_cndmask_b32_e64 v82, v88, v82, s[58:59]
	v_xor_b32_e32 v91, v91, v95
	v_alignbit_b32 v87, v83, v82, v93
	v_cndmask_b32_e64 v83, v87, v83, s[60:61]
	v_ffbh_u32_e32 v88, v91
	v_alignbit_b32 v87, v89, v83, 30
	v_min_u32_e32 v88, 32, v88
	v_alignbit_b32 v82, v83, v82, 30
	v_xor_b32_e32 v87, v87, v95
	v_sub_u32_e32 v89, 31, v88
	v_xor_b32_e32 v82, v82, v95
	v_alignbit_b32 v90, v91, v87, v89
	v_alignbit_b32 v82, v87, v82, v89
	v_alignbit_b32 v83, v90, v82, 9
	v_ffbh_u32_e32 v87, v83
	v_min_u32_e32 v87, 32, v87
	v_lshrrev_b32_e32 v92, 29, v81
	v_not_b32_e32 v89, v87
	v_alignbit_b32 v82, v83, v82, v89
	v_lshlrev_b32_e32 v83, 31, v92
	v_or_b32_e32 v89, 0x33000000, v83
	v_add_lshl_u32 v87, v87, v88, 23
	v_lshrrev_b32_e32 v82, 9, v82
	v_sub_u32_e32 v87, v89, v87
	v_or_b32_e32 v83, 0.5, v83
	v_lshlrev_b32_e32 v88, 23, v88
	v_or_b32_e32 v82, v87, v82
	v_lshrrev_b32_e32 v87, 9, v90
	v_sub_u32_e32 v83, v83, v88
	v_or_b32_e32 v83, v87, v83
	v_mul_f32_e32 v87, 0x3fc90fda, v83
	v_fma_f32 v88, v83, s27, -v87
	v_fmac_f32_e32 v88, 0x33a22168, v83
	v_fmac_f32_e32 v88, 0x3fc90fda, v82
	v_lshrrev_b32_e32 v81, 30, v81
	v_add_f32_e32 v82, v87, v88
	v_add_u32_e32 v81, v94, v81

; __device__ __forceinline__ void phase_prep0() {
;     ...
;         float cs[8], sn[8];
; #pragma unroll
;         for (int e = 0; e < 8; ++e) { cs[e] = 1.f; sn[e] = 0.f; }
;         if (!isc) {
; #pragma unroll
;             for (int e = 0; e < 8; ++e) { const int i = 8 * (l7 & 3) + e, mm = i & 15; const float pos = (float)(i < 16 ? grow : gcol); const float ang = pos * exp2f(-(float)mm * 0.8304820237218406f); cs[e] = cosf(ang); sn[e] = sinf(ang); } }
.LBB0_349:
	s_or_b64 exec, exec, s[8:9]
	v_mul_f32_e32 v168, v169, v169
	v_fmamk_f32 v170, v168, 0xb94c1982, v103
	v_fmaak_f32 v170, v168, v170, 0xbe2aaa9d
	v_mul_f32_e32 v170, v168, v170
	v_fmac_f32_e32 v169, v169, v170
	v_fmamk_f32 v170, v168, 0x37d75334, v153
	v_fmaak_f32 v170, v168, v170, 0x3d2aabf7
	v_fmaak_f32 v170, v168, v170, 0xbf000004
	v_fma_f32 v168, v168, v170, 1.0
	v_and_b32_e32 v170, 1, v85
	v_cmp_eq_u32_e32 vcc, 0, v170
	v_lshlrev_b32_e32 v85, 30, v85
	s_nop 0
	v_cndmask_b32_e64 v168, -v169, v168, vcc
	v_cmp_lg_f32_e32 vcc, s29, v84
	v_mul_f32_e32 v84, v166, v166
	v_bitop3_b32 v85, v85, v168, s28 bitop3:0x6c
	v_fmamk_f32 v168, v84, 0xb94c1982, v103
	v_fmaak_f32 v168, v84, v168, 0xbe2aaa9d
	v_mul_f32_e32 v168, v84, v168
	v_fmac_f32_e32 v166, v166, v168
	v_fmamk_f32 v168, v84, 0x37d75334, v153
	v_fmaak_f32 v168, v84, v168, 0x3d2aabf7
	v_fmaak_f32 v168, v84, v168, 0xbf000004
	v_fma_f32 v84, v84, v168, 1.0
	v_and_b32_e32 v168, 1, v165
	v_cmp_eq_u32_e64 s[54:55], 0, v168
	v_lshlrev_b32_e32 v165, 30, v165
	v_cndmask_b32_e32 v85, v157, v85, vcc
	v_cndmask_b32_e64 v84, v84, v166, s[54:55]
	v_bitop3_b32 v84, v165, v84, s28 bitop3:0x6c
	v_cmp_lg_f32_e64 s[54:55], s29, v86
	s_nop 1
	v_cndmask_b32_e64 v86, v157, v84, s[54:55]
	v_mul_f32_e32 v84, v164, v164
	v_fmamk_f32 v165, v84, 0xb94c1982, v103
	v_fmaak_f32 v165, v84, v165, 0xbe2aaa9d
	v_mul_f32_e32 v165, v84, v165
	v_fmac_f32_e32 v164, v164, v165
	v_fmamk_f32 v165, v84, 0x37d75334, v153
	v_fmaak_f32 v165, v84, v165, 0x3d2aabf7
	v_fmaak_f32 v165, v84, v165, 0xbf000004
	v_fma_f32 v84, v84, v165, 1.0
	v_and_b32_e32 v165, 1, v135
	v_cmp_eq_u32_e64 s[56:57], 0, v165
	v_lshlrev_b32_e32 v135, 30, v135
	s_nop 0
	v_cndmask_b32_e64 v84, -v164, v84, s[56:57]
	v_bitop3_b32 v84, v135, v84, s28 bitop3:0x6c
	v_mul_f32_e32 v135, v134, v134
	v_fmamk_f32 v164, v135, 0xb94c1982, v103
	v_fmaak_f32 v164, v135, v164, 0xbe2aaa9d
	v_mul_f32_e32 v164, v135, v164
	v_fmac_f32_e32 v134, v134, v164
	v_fmamk_f32 v164, v135, 0x37d75334, v153
	v_fmaak_f32 v164, v135, v164, 0x3d2aabf7
	v_fmaak_f32 v164, v135, v164, 0xbf000004
	v_fma_f32 v135, v135, v164, 1.0
	v_and_b32_e32 v164, 1, v91
	v_cndmask_b32_e64 v84, v157, v84, s[54:55]
	v_cmp_eq_u32_e64 s[54:55], 0, v164
	v_lshlrev_b32_e32 v91, 30, v91
	s_nop 0
	v_cndmask_b32_e64 v134, v135, v134, s[54:55]
	v_cmp_lg_f32_e64 s[54:55], s29, v89
	v_mul_f32_e32 v89, v133, v133
	v_bitop3_b32 v91, v91, v134, s28 bitop3:0x6c
	v_fmamk_f32 v134, v89, 0xb94c1982, v103
	v_fmaak_f32 v134, v89, v134, 0xbe2aaa9d
	v_mul_f32_e32 v134, v89, v134
	v_fmac_f32_e32 v133, v133, v134
	v_fmamk_f32 v134, v89, 0x37d75334, v153
	v_fmaak_f32 v134, v89, v134, 0x3d2aabf7
	v_fmaak_f32 v134, v89, v134, 0xbf000004
	v_fma_f32 v89, v89, v134, 1.0
	v_and_b32_e32 v134, 1, v132
	v_cmp_eq_u32_e64 s[56:57], 0, v134
	v_lshlrev_b32_e32 v132, 30, v132
	v_cndmask_b32_e64 v91, v157, v91, s[54:55]
	v_cndmask_b32_e64 v89, -v133, v89, s[56:57]
	v_bitop3_b32 v89, v132, v89, s28 bitop3:0x6c
	v_mul_f32_e32 v132, v131, v131
	v_fmamk_f32 v133, v132, 0xb94c1982, v103
	v_fmaak_f32 v133, v132, v133, 0xbe2aaa9d
	v_mul_f32_e32 v133, v132, v133
	v_fmac_f32_e32 v131, v131, v133
	v_fmamk_f32 v133, v132, 0x37d75334, v153
	v_fmaak_f32 v133, v132, v133, 0x3d2aabf7
	v_fmaak_f32 v133, v132, v133, 0xbf000004
	v_fma_f32 v132, v132, v133, 1.0
	v_and_b32_e32 v133, 1, v90
	v_cndmask_b32_e64 v89, v157, v89, s[54:55]
	v_cmp_eq_u32_e64 s[54:55], 0, v133
	v_lshlrev_b32_e32 v90, 30, v90
	s_nop 0
	v_cndmask_b32_e64 v131, v132, v131, s[54:55]
	v_cmp_lg_f32_e64 s[54:55], s29, v88
	v_mul_f32_e32 v88, v130, v130
	v_bitop3_b32 v90, v90, v131, s28 bitop3:0x6c
	v_fmamk_f32 v131, v88, 0xb94c1982, v103
	v_fmaak_f32 v131, v88, v131, 0xbe2aaa9d
	v_mul_f32_e32 v131, v88, v131
	v_fmac_f32_e32 v130, v130, v131
	v_fmamk_f32 v131, v88, 0x37d75334, v153
	v_fmaak_f32 v131, v88, v131, 0x3d2aabf7
	v_fmaak_f32 v131, v88, v131, 0xbf000004
	v_fma_f32 v88, v88, v131, 1.0
	v_and_b32_e32 v131, 1, v129
	v_cmp_eq_u32_e64 s[56:57], 0, v131
	v_lshlrev_b32_e32 v129, 30, v129
	v_cndmask_b32_e64 v90, v157, v90, s[54:55]
	v_cndmask_b32_e64 v88, -v130, v88, s[56:57]
	v_bitop3_b32 v88, v129, v88, s28 bitop3:0x6c
	v_mul_f32_e32 v129, v128, v128
	v_fmamk_f32 v130, v129, 0xb94c1982, v103
	v_fmaak_f32 v130, v129, v130, 0xbe2aaa9d
	v_mul_f32_e32 v130, v129, v130
	v_fmac_f32_e32 v128, v128, v130
	v_fmamk_f32 v130, v129, 0x37d75334, v153
	v_fmaak_f32 v130, v129, v130, 0x3d2aabf7
	v_fmaak_f32 v130, v129, v130, 0xbf000004
	v_fma_f32 v129, v129, v130, 1.0
	v_and_b32_e32 v130, 1, v95
	v_cndmask_b32_e64 v88, v157, v88, s[54:55]
	v_cmp_eq_u32_e64 s[54:55], 0, v130
	v_lshlrev_b32_e32 v95, 30, v95
	s_nop 0
	v_cndmask_b32_e64 v128, v129, v128, s[54:55]
	v_cmp_lg_f32_e64 s[54:55], s29, v93
	v_mul_f32_e32 v93, v127, v127
	v_bitop3_b32 v95, v95, v128, s28 bitop3:0x6c
	v_fmamk_f32 v128, v93, 0xb94c1982, v103
	v_fmaak_f32 v128, v93, v128, 0xbe2aaa9d
	v_mul_f32_e32 v128, v93, v128
	v_fmac_f32_e32 v127, v127, v128
	v_fmamk_f32 v128, v93, 0x37d75334, v153
	v_fmaak_f32 v128, v93, v128, 0x3d2aabf7
	v_fmaak_f32 v128, v93, v128, 0xbf000004
	v_fma_f32 v93, v93, v128, 1.0
	v_and_b32_e32 v128, 1, v126
	v_cmp_eq_u32_e64 s[56:57], 0, v128
	v_lshlrev_b32_e32 v126, 30, v126
	v_cndmask_b32_e64 v95, v157, v95, s[54:55]
	v_cndmask_b32_e64 v93, -v127, v93, s[56:57]
	v_bitop3_b32 v93, v126, v93, s28 bitop3:0x6c
	v_mul_f32_e32 v126, v125, v125
	v_fmamk_f32 v127, v126, 0xb94c1982, v103
	v_fmaak_f32 v127, v126, v127, 0xbe2aaa9d
	v_mul_f32_e32 v127, v126, v127
	v_fmac_f32_e32 v125, v125, v127
	v_fmamk_f32 v127, v126, 0x37d75334, v153
	v_fmaak_f32 v127, v126, v127, 0x3d2aabf7
	v_fmaak_f32 v127, v126, v127, 0xbf000004
; __device__ __forceinline__ void phase_prep0() {
;     ...
;         float cs[8], sn[8];
; #pragma unroll
;         for (int e = 0; e < 8; ++e) { cs[e] = 1.f; sn[e] = 0.f; }
;         if (!isc) {
; #pragma unroll
;             for (int e = 0; e < 8; ++e) { const int i = 8 * (l7 & 3) + e, mm = i & 15; const float pos = (float)(i < 16 ? grow : gcol); const float ang = pos * exp2f(-(float)mm * 0.8304820237218406f); cs[e] = cosf(ang); sn[e] = sinf(ang); } }
	v_fma_f32 v126, v126, v127, 1.0
	v_and_b32_e32 v127, 1, v94
	v_cndmask_b32_e64 v93, v157, v93, s[54:55]
	v_cmp_eq_u32_e64 s[54:55], 0, v127
	v_lshlrev_b32_e32 v94, 30, v94
	s_nop 0
	v_cndmask_b32_e64 v125, v126, v125, s[54:55]
	v_cmp_lg_f32_e64 s[54:55], s29, v92
	v_mul_f32_e32 v92, v124, v124
	v_bitop3_b32 v94, v94, v125, s28 bitop3:0x6c
	v_fmamk_f32 v125, v92, 0xb94c1982, v103
	v_fmaak_f32 v125, v92, v125, 0xbe2aaa9d
	v_mul_f32_e32 v125, v92, v125
	v_fmac_f32_e32 v124, v124, v125
	v_fmamk_f32 v125, v92, 0x37d75334, v153
	v_fmaak_f32 v125, v92, v125, 0x3d2aabf7
	v_fmaak_f32 v125, v92, v125, 0xbf000004
	v_fma_f32 v92, v92, v125, 1.0
	v_and_b32_e32 v125, 1, v123
	v_cmp_eq_u32_e64 s[56:57], 0, v125
	v_lshlrev_b32_e32 v123, 30, v123
	v_cndmask_b32_e64 v94, v157, v94, s[54:55]
	v_cndmask_b32_e64 v92, -v124, v92, s[56:57]
	v_bitop3_b32 v92, v123, v92, s28 bitop3:0x6c
	v_mul_f32_e32 v123, v122, v122
	v_fmamk_f32 v124, v123, 0xb94c1982, v103
	v_fmaak_f32 v124, v123, v124, 0xbe2aaa9d
	v_mul_f32_e32 v124, v123, v124
	v_fmac_f32_e32 v122, v122, v124
	v_fmamk_f32 v124, v123, 0x37d75334, v153
	v_fmaak_f32 v124, v123, v124, 0x3d2aabf7
	v_fmaak_f32 v124, v123, v124, 0xbf000004
	v_fma_f32 v123, v123, v124, 1.0
	v_and_b32_e32 v124, 1, v99
	v_cndmask_b32_e64 v92, v157, v92, s[54:55]
	v_cmp_eq_u32_e64 s[54:55], 0, v124
	v_lshlrev_b32_e32 v99, 30, v99
	s_nop 0
	v_cndmask_b32_e64 v122, v123, v122, s[54:55]
	v_cmp_lg_f32_e64 s[54:55], s29, v96
	v_mul_f32_e32 v96, v98, v98
	v_bitop3_b32 v99, v99, v122, s28 bitop3:0x6c
	v_fmamk_f32 v122, v96, 0xb94c1982, v103
	v_fmaak_f32 v122, v96, v122, 0xbe2aaa9d
	v_mul_f32_e32 v122, v96, v122
	v_fmac_f32_e32 v98, v98, v122
	v_fmamk_f32 v122, v96, 0x37d75334, v153
	v_fmaak_f32 v122, v96, v122, 0x3d2aabf7
	v_fmaak_f32 v122, v96, v122, 0xbf000004
	v_fma_f32 v96, v96, v122, 1.0
	v_and_b32_e32 v122, 1, v97
	v_cmp_eq_u32_e64 s[56:57], 0, v122
	v_lshlrev_b32_e32 v97, 30, v97
	v_cndmask_b32_e64 v99, v157, v99, s[54:55]
	v_cndmask_b32_e64 v96, -v98, v96, s[56:57]
	v_bitop3_b32 v96, v97, v96, s28 bitop3:0x6c
	v_cndmask_b32_e64 v97, v157, v96, s[54:55]
	v_mul_f32_e32 v96, v87, v87
	v_fmamk_f32 v98, v96, 0xb94c1982, v103
	v_fmaak_f32 v98, v96, v98, 0xbe2aaa9d
	v_mul_f32_e32 v98, v96, v98
	v_fmac_f32_e32 v87, v87, v98
	v_fmamk_f32 v98, v96, 0x37d75334, v153
	v_fmaak_f32 v98, v96, v98, 0x3d2aabf7
	v_fmaak_f32 v98, v96, v98, 0xbf000004
	v_fma_f32 v96, v96, v98, 1.0
	v_and_b32_e32 v98, 1, v83
	v_cmp_eq_u32_e64 s[54:55], 0, v98
	v_lshlrev_b32_e32 v83, 30, v83
	s_nop 0
	v_cndmask_b32_e64 v87, v96, v87, s[54:55]
	v_bitop3_b32 v83, v83, v87, s28 bitop3:0x6c
	v_cmp_lg_f32_e64 s[54:55], s29, v80
	v_mul_f32_e32 v80, v82, v82
	s_nop 0
	v_cndmask_b32_e64 v98, v157, v83, s[54:55]
	v_fmamk_f32 v83, v80, 0xb94c1982, v103
	v_fmaak_f32 v83, v80, v83, 0xbe2aaa9d
	v_mul_f32_e32 v83, v80, v83
	v_fmac_f32_e32 v82, v82, v83
	v_fmamk_f32 v83, v80, 0x37d75334, v153
	v_fmaak_f32 v83, v80, v83, 0x3d2aabf7
	v_fmaak_f32 v83, v80, v83, 0xbf000004
	v_fma_f32 v80, v80, v83, 1.0
	v_and_b32_e32 v83, 1, v81
	v_cmp_eq_u32_e64 s[56:57], 0, v83
	v_lshlrev_b32_e32 v81, 30, v81
	s_nop 0
	v_cndmask_b32_e64 v80, -v82, v80, s[56:57]
	v_bitop3_b32 v80, v81, v80, s28 bitop3:0x6c
	v_cndmask_b32_e64 v96, v157, v80, s[54:55]
	v_mul_f32_e32 v80, v167, v167
	v_fmamk_f32 v81, v80, 0xb94c1982, v103
	v_fmaak_f32 v81, v80, v81, 0xbe2aaa9d
	v_mul_f32_e32 v81, v80, v81
	v_fmac_f32_e32 v167, v167, v81
	v_fmamk_f32 v81, v80, 0x37d75334, v153
	v_fmaak_f32 v81, v80, v81, 0x3d2aabf7
	v_fmaak_f32 v81, v80, v81, 0xbf000004
	v_fma_f32 v80, v80, v81, 1.0
	v_and_b32_e32 v81, 1, v104
	v_cmp_eq_u32_e64 s[54:55], 0, v81
	v_lshlrev_b32_e32 v81, 30, v104
	s_nop 0
	v_cndmask_b32_e64 v80, v80, v167, s[54:55]
	v_bitop3_b32 v80, v81, v80, s28 bitop3:0x6c
	v_cndmask_b32_e32 v87, v157, v80, vcc
	s_bitcmp1_b32 s98, 0
	s_cbranch_scc1 .Lprep_save_b
	v_mov_b32_e32 v186, v84
	v_mov_b32_e32 v187, v85
	v_mov_b32_e32 v188, v86
	v_mov_b32_e32 v189, v87
	v_mov_b32_e32 v190, v88
	v_mov_b32_e32 v191, v89
	v_mov_b32_e32 v192, v90
	v_mov_b32_e32 v193, v91
	v_mov_b32_e32 v194, v92
	v_mov_b32_e32 v195, v93
	v_mov_b32_e32 v196, v94
	v_mov_b32_e32 v197, v95
	v_mov_b32_e32 v198, v96
	v_mov_b32_e32 v199, v97
	v_mov_b32_e32 v200, v98
	v_mov_b32_e32 v201, v99
	s_branch .LBB0_350
.Lprep_save_b:
	v_mov_b32_e32 v202, v84
	v_mov_b32_e32 v203, v85
	v_mov_b32_e32 v204, v86
	v_mov_b32_e32 v205, v87
	v_mov_b32_e32 v206, v88
	v_mov_b32_e32 v207, v89
	v_mov_b32_e32 v208, v90
	v_mov_b32_e32 v209, v91
	v_mov_b32_e32 v210, v92
	v_mov_b32_e32 v211, v93
	v_mov_b32_e32 v212, v94
	v_mov_b32_e32 v213, v95
	v_mov_b32_e32 v214, v96
	v_mov_b32_e32 v215, v97
	v_mov_b32_e32 v216, v98
	v_mov_b32_e32 v217, v99
	s_branch .LBB0_350
; __device__ __forceinline__ float red8(float x) { x += dppf<0xB1>(x); x += dppf<0x4E>(x); x += dppf<0x141>(x); return x; }
; __device__ __forceinline__ void phase_prep0() {
;     ...
;         float cs[8], sn[8];
; #pragma unroll
;         for (int e = 0; e < 8; ++e) { cs[e] = 1.f; sn[e] = 0.f; }
;         if (!isc) {
; #pragma unroll
;             for (int e = 0; e < 8; ++e) { const int i = 8 * (l7 & 3) + e, mm = i & 15; const float pos = (float)(i < 16 ? grow : gcol); const float ang = pos * exp2f(-(float)mm * 0.8304820237218406f); cs[e] = cosf(ang); sn[e] = sinf(ang); } }
;         const int kvpos = isc ? SEQ + s : t;
; #pragma unroll
;         for (int p = 0; p < 3; ++p) {
;             const u32x4 raw = *(const u32x4*)(prow + p * 512 + lane * 8); float x[8]; unpack8(raw, x);
;             float ss = 0.f;
; #pragma unroll
;             for (int e = 0; e < 8; ++e) ss += x[e] * x[e];
;             ss = red8(ss); const float rs = rsqrtf(ss * (1.f / 64.f) + 1e-6f);
;             float y[8];
; #pragma unroll
;             for (int e = 0; e < 8; ++e) y[e] = x[e] * rs * (p < 2 ? qn[e] : kn[e]);
;             if (!isc) {
; #pragma unroll
;                 for (int e = 0; e < 8; ++e) { const float o = __shfl_xor(y[e], 4); y[e] = (l7 < 4) ? y[e] * cs[e] - o * sn[e] : y[e] * cs[e] + o * sn[e]; } }
.Lprep_reuse:
	s_bitcmp1_b32 s98, 0
	s_cbranch_scc1 .Lprep_load_b
	v_mov_b32_e32 v84, v186
	v_mov_b32_e32 v85, v187
	v_mov_b32_e32 v86, v188
	v_mov_b32_e32 v87, v189
	v_mov_b32_e32 v88, v190
	v_mov_b32_e32 v89, v191
	v_mov_b32_e32 v90, v192
	v_mov_b32_e32 v91, v193
	v_mov_b32_e32 v92, v194
	v_mov_b32_e32 v93, v195
	v_mov_b32_e32 v94, v196
	v_mov_b32_e32 v95, v197
	v_mov_b32_e32 v96, v198
	v_mov_b32_e32 v97, v199
	v_mov_b32_e32 v98, v200
	v_mov_b32_e32 v99, v201
	s_branch .LBB0_350
.Lprep_load_b:
	v_mov_b32_e32 v84, v202
	v_mov_b32_e32 v85, v203
	v_mov_b32_e32 v86, v204
	v_mov_b32_e32 v87, v205
	v_mov_b32_e32 v88, v206
	v_mov_b32_e32 v89, v207
	v_mov_b32_e32 v90, v208
	v_mov_b32_e32 v91, v209
	v_mov_b32_e32 v92, v210
	v_mov_b32_e32 v93, v211
	v_mov_b32_e32 v94, v212
	v_mov_b32_e32 v95, v213
	v_mov_b32_e32 v96, v214
	v_mov_b32_e32 v97, v215
	v_mov_b32_e32 v98, v216
	v_mov_b32_e32 v99, v217
.LBB0_350:
	s_or_b64 exec, exec, s[14:15]
	s_add_u32 s98, s98, 1
	v_lshl_add_u64 v[122:123], v[120:121], 0, v[66:67]
	v_add_co_u32_e32 v80, vcc, 0x11000000, v122
	s_nop 1
	v_addc_co_u32_e32 v81, vcc, 0, v123, vcc
	global_load_dwordx4 v[80:83], v[80:81], off
	s_waitcnt vmcnt(0)
	v_lshlrev_b32_e32 v124, 16, v80
	v_and_b32_e32 v125, 0xffff0000, v80
	v_lshlrev_b32_e32 v80, 16, v81
	v_and_b32_e32 v81, 0xffff0000, v81
	v_pk_mul_f32 v[128:129], v[124:125], v[124:125]
	v_pk_mul_f32 v[130:131], v[80:81], v[80:81]
	v_add_f32_e32 v104, v128, v129
	v_lshlrev_b32_e32 v126, 16, v82
	v_and_b32_e32 v127, 0xffff0000, v82
	v_add_f32_e32 v104, v130, v104
	v_pk_mul_f32 v[132:133], v[126:127], v[126:127]
	v_add_f32_e32 v104, v131, v104
	v_lshlrev_b32_e32 v82, 16, v83
	v_and_b32_e32 v83, 0xffff0000, v83
	v_add_f32_e32 v104, v132, v104
	v_pk_mul_f32 v[134:135], v[82:83], v[82:83]
	v_add_f32_e32 v104, v133, v104
	v_add_f32_e32 v104, v134, v104
	v_add_f32_e32 v104, v135, v104
	s_nop 1
	v_add_f32_dpp v104, v104, v104 quad_perm:[1,0,3,2] row_mask:0xf bank_mask:0xf bound_ctrl:1
	s_nop 1
	v_add_f32_dpp v104, v104, v104 quad_perm:[2,3,0,1] row_mask:0xf bank_mask:0xf bound_ctrl:1
	s_nop 1
	v_add_f32_dpp v104, v104, v104 row_half_mirror row_mask:0xf bank_mask:0xf bound_ctrl:1
	v_fmamk_f32 v104, v104, 0x3c800000, v154
	v_mul_f32_e32 v128, 0x4b800000, v104
	v_cmp_gt_f32_e32 vcc, s1, v104
	s_nop 1
	v_cndmask_b32_e32 v104, v104, v128, vcc
	v_rsq_f32_e32 v128, v104
	v_mbcnt_hi_u32_b32 v104, -1, v220
	v_mul_f32_e32 v129, 0x45800000, v128
	v_cndmask_b32_e32 v128, v128, v129, vcc
	v_pk_mul_f32 v[124:125], v[128:129], v[124:125] op_sel_hi:[0,1]
	v_pk_mul_f32 v[130:131], v[128:129], v[80:81] op_sel_hi:[0,1]
	v_pk_mul_f32 v[126:127], v[128:129], v[126:127] op_sel_hi:[0,1]
	v_pk_mul_f32 v[128:129], v[128:129], v[82:83] op_sel_hi:[0,1]
	v_pk_mul_f32 v[80:81], v[52:53], v[124:125]
	v_pk_mul_f32 v[82:83], v[54:55], v[130:131]
	v_pk_mul_f32 v[124:125], v[48:49], v[126:127]
	v_pk_mul_f32 v[126:127], v[50:51], v[128:129]
	v_mov_b32_e32 v130, v80
	v_mov_b32_e32 v132, v81
	v_mov_b32_e32 v131, v82
	v_mov_b32_e32 v133, v83
	v_mov_b32_e32 v128, v124
	v_mov_b32_e32 v134, v125
	v_mov_b32_e32 v129, v126
	v_mov_b32_e32 v135, v127
	s_and_saveexec_b64 s[8:9], s[50:51]
	s_cbranch_execz .LBB0_352
	v_and_b32_e32 v129, 64, v104
	v_xor_b32_e32 v128, 4, v104
	v_add_u32_e32 v129, 64, v129
	v_cmp_lt_i32_e32 vcc, v128, v129
	s_nop 1
	v_cndmask_b32_e32 v128, v104, v128, vcc
	v_lshlrev_b32_e32 v135, 2, v128
	ds_bpermute_b32 v128, v135, v80
	ds_bpermute_b32 v129, v135, v81
	ds_bpermute_b32 v130, v135, v82
	ds_bpermute_b32 v131, v135, v83
	ds_bpermute_b32 v132, v135, v124
	ds_bpermute_b32 v133, v135, v125
	ds_bpermute_b32 v134, v135, v126
	ds_bpermute_b32 v135, v135, v127
	s_waitcnt lgkmcnt(6)
	v_pk_mul_f32 v[128:129], v[98:99], v[128:129]
	s_waitcnt lgkmcnt(4)
	v_pk_mul_f32 v[130:131], v[94:95], v[130:131]
	s_waitcnt lgkmcnt(2)
	v_pk_mul_f32 v[132:133], v[90:91], v[132:133]
	v_cndmask_b32_e64 v165, v129, -v129, s[38:39]
	s_waitcnt lgkmcnt(0)
	v_pk_mul_f32 v[134:135], v[86:87], v[134:135]
	v_cndmask_b32_e64 v164, v128, -v128, s[38:39]
	v_cndmask_b32_e64 v131, v131, -v131, s[38:39]
	v_cndmask_b32_e64 v130, v130, -v130, s[38:39]
	v_cndmask_b32_e64 v129, v133, -v133, s[38:39]
	v_cndmask_b32_e64 v128, v132, -v132, s[38:39]
	v_cndmask_b32_e64 v133, v135, -v135, s[38:39]
	v_cndmask_b32_e64 v132, v134, -v134, s[38:39]
	v_pk_fma_f32 v[126:127], v[84:85], v[126:127], v[132:133]
	v_pk_fma_f32 v[128:129], v[88:89], v[124:125], v[128:129]
	v_pk_fma_f32 v[82:83], v[92:93], v[82:83], v[130:131]
	v_pk_fma_f32 v[130:131], v[96:97], v[80:81], v[164:165]
	v_mov_b32_e32 v133, v83
	v_mov_b32_e32 v132, v131
	v_mov_b32_e32 v131, v82
	v_mov_b32_e32 v134, v129
	v_mov_b32_e32 v129, v126
	v_mov_b32_e32 v135, v127

; __global__ void __launch_bounds__(512, 2) fwd_megakernel(Args a) {
	.amdhsa_kernel _Z14fwd_megakernel4Args
		.amdhsa_group_segment_fixed_size 0
		.amdhsa_private_segment_fixed_size 0
		.amdhsa_kernarg_size 592
		.amdhsa_user_sgpr_count 2
		.amdhsa_user_sgpr_dispatch_ptr 0
		.amdhsa_user_sgpr_queue_ptr 0
		.amdhsa_user_sgpr_kernarg_segment_ptr 1
		.amdhsa_user_sgpr_dispatch_id 0
		.amdhsa_user_sgpr_kernarg_preload_length 0
		.amdhsa_user_sgpr_kernarg_preload_offset 0
		.amdhsa_user_sgpr_private_segment_size 0
		.amdhsa_uses_dynamic_stack 0
		.amdhsa_enable_private_segment 0
		.amdhsa_system_sgpr_workgroup_id_x 1
		.amdhsa_system_sgpr_workgroup_id_y 0
		.amdhsa_system_sgpr_workgroup_id_z 0
		.amdhsa_system_sgpr_workgroup_info 0
		.amdhsa_system_vgpr_workitem_id 2
		.amdhsa_next_free_vgpr 256
		.amdhsa_next_free_sgpr 100
		.amdhsa_accum_offset 256
		.amdhsa_reserve_vcc 1
		.amdhsa_float_round_mode_32 0
		.amdhsa_float_round_mode_16_64 0
		.amdhsa_float_denorm_mode_32 3
		.amdhsa_float_denorm_mode_16_64 3
		.amdhsa_dx10_clamp 1
		.amdhsa_ieee_mode 1
		.amdhsa_fp16_overflow 0
		.amdhsa_tg_split 0
		.amdhsa_exception_fp_ieee_invalid_op 0
		.amdhsa_exception_fp_denorm_src 0
		.amdhsa_exception_fp_ieee_div_zero 0
		.amdhsa_exception_fp_ieee_overflow 0
		.amdhsa_exception_fp_ieee_underflow 0
		.amdhsa_exception_fp_ieee_inexact 0
		.amdhsa_exception_int_div_zero 0
	.end_amdhsa_kernel

; __global__ void __launch_bounds__(512, 2) fwd_megakernel(Args a) {
amdhsa.kernels:
  - .agpr_count:     0
    .args:
      - .offset:         0
        .size:           336
        .value_kind:     by_value
      - .offset:         336
        .size:           4
        .value_kind:     hidden_block_count_x
      - .offset:         340
        .size:           4
        .value_kind:     hidden_block_count_y
      - .offset:         344
        .size:           4
        .value_kind:     hidden_block_count_z
      - .offset:         348
        .size:           2
        .value_kind:     hidden_group_size_x
      - .offset:         350
        .size:           2
        .value_kind:     hidden_group_size_y
      - .offset:         352
        .size:           2
        .value_kind:     hidden_group_size_z
      - .offset:         354
        .size:           2
        .value_kind:     hidden_remainder_x
      - .offset:         356
        .size:           2
        .value_kind:     hidden_remainder_y
      - .offset:         358
        .size:           2
        .value_kind:     hidden_remainder_z
      - .offset:         376
        .size:           8
        .value_kind:     hidden_global_offset_x
      - .offset:         384
        .size:           8
        .value_kind:     hidden_global_offset_y
      - .offset:         392
        .size:           8
        .value_kind:     hidden_global_offset_z
      - .offset:         400
        .size:           2
        .value_kind:     hidden_grid_dims
      - .offset:         424
        .size:           8
        .value_kind:     hidden_multigrid_sync_arg
      - .offset:         456
        .size:           4
        .value_kind:     hidden_dynamic_lds_size
    .group_segment_fixed_size: 0
    .kernarg_segment_align: 8
    .kernarg_segment_size: 592
    .language:       OpenCL C
    .language_version:
      - 2
      - 0
    .max_flat_workgroup_size: 512
    .name:           _Z14fwd_megakernel4Args
    .private_segment_fixed_size: 0
    .sgpr_count:     106
    .sgpr_spill_count: 125
    .symbol:         _Z14fwd_megakernel4Args.kd
    .uniform_work_group_size: 1
    .uses_dynamic_stack: false
    .vgpr_count:     256
    .vgpr_spill_count: 0
    .wavefront_size: 64
